# selected-branch walk: per-step block descriptors fetched with v_readlane from a VGPR-resident copy of the step list instead of ds_read + lgkmcnt(0) + v_readfirstlane each step
# baseline (speedup 1.0000x reference)
; __device__ __forceinline__ unsigned cvt_pk_bf16(float lo, float hi) { f32x2 v = {lo, hi}; bf16x2_t b = __builtin_convertvector(v, bf16x2_t); return __builtin_bit_cast(unsigned, b); }
; __device__ __forceinline__ float bf2f(unsigned short b) { return __uint_as_float(((unsigned)b) << 16); }
; __device__ __forceinline__ void nsa_unit(int unit, const bf16_t* proj, const bf16_t* kc, const bf16_t* vc, const bf16_t* gn, const float* cs, const float* sn, ...
;     ...
;     for (int s2 = 0; s2 < 2; ++s2) {
;         const int d = 32 * s2 + 8 * kq; f32x4 c[2], sv[2];
;         c[0] = *(const f32x4*)(cs + (size_t)tc * 64 + d); c[1] = *(const f32x4*)(cs + (size_t)tc * 64 + d + 4);
;         sv[0] = *(const f32x4*)(sn + (size_t)tc * 64 + d); sv[1] = *(const f32x4*)(sn + (size_t)tc * 64 + d + 4);
;         float o1[8], o2[8];
; #pragma unroll
;         for (int j = 0; j < 8; ++j) { const float x1 = bf2f((unsigned short)qf[s2][j]), x2 = bf2f((unsigned short)qf[s2 + 2][j]), cc = c[j >> 2][j & 3], ss = sv[j >> 2][j & 3];
;             o1[j] = x1 * cc - x2 * ss; o2[j] = x2 * cc + x1 * ss; }
;         u32x4 w1, w2; w1.x = cvt_pk_bf16(o1[0], o1[1]); w1.y = cvt_pk_bf16(o1[2], o1[3]); w1.z = cvt_pk_bf16(o1[4], o1[5]); w1.w = cvt_pk_bf16(o1[6], o1[7]);
;         w2.x = cvt_pk_bf16(o2[0], o2[1]); w2.y = cvt_pk_bf16(o2[2], o2[3]); w2.z = cvt_pk_bf16(o2[4], o2[5]); w2.w = cvt_pk_bf16(o2[6], o2[7]);
;         qf[s2] = __builtin_bit_cast(bf16x8, w1); qf[s2 + 2] = __builtin_bit_cast(bf16x8, w2);
;     }
;     ...
;     i64_t q8[4];
; #pragma unroll
;     for (int s2 = 0; s2 < 4; ++s2) { f32x4 a, b;
; #pragma unroll
;         for (int j = 0; j < 4; ++j) { a[j] = bf2f((unsigned short)qf[s2][j]) * SL2; b[j] = bf2f((unsigned short)qf[s2][4 + j]) * SL2; }
;         q8[s2] = __builtin_bit_cast(i64_t, pack8_fp8(a, b)); }
.LBB0_959:
	s_or_b64 exec, exec, s[12:13]
	v_and_b32_e32 v51, 0xffff0000, v14
	v_lshlrev_b32_e32 v50, 16, v14
	v_and_b32_e32 v53, 0xffff0000, v10
	v_lshlrev_b32_e32 v52, 16, v10
	s_waitcnt vmcnt(4)
	v_pk_mul_f32 v[54:55], v[46:47], v[52:53]
	v_pk_mul_f32 v[46:47], v[46:47], v[50:51]
	v_pk_fma_f32 v[54:55], v[42:43], v[50:51], v[54:55] neg_lo:[0,0,1] neg_hi:[0,0,1]
	v_pk_fma_f32 v[42:43], v[42:43], v[52:53], v[46:47]
	v_and_b32_e32 v47, 0xffff0000, v15
	v_lshlrev_b32_e32 v46, 16, v15
	v_and_b32_e32 v15, 0xffff0000, v11
	v_lshlrev_b32_e32 v14, 16, v11
	v_pk_mul_f32 v[10:11], v[48:49], v[14:15]
	v_cvt_pk_bf16_f32 v0, v54, v55
	v_pk_fma_f32 v[10:11], v[44:45], v[46:47], v[10:11] neg_lo:[0,0,1] neg_hi:[0,0,1]
	v_pk_mul_f32 v[46:47], v[48:49], v[46:47]
	v_mov_b32_e32 v79, v1
	v_pk_fma_f32 v[14:15], v[44:45], v[14:15], v[46:47]
	v_and_b32_e32 v45, 0xffff0000, v16
	v_lshlrev_b32_e32 v44, 16, v16
	v_and_b32_e32 v47, 0xffff0000, v12
	v_lshlrev_b32_e32 v46, 16, v12
	v_pk_mul_f32 v[48:49], v[38:39], v[46:47]
	v_pk_mul_f32 v[38:39], v[38:39], v[44:45]
	v_pk_fma_f32 v[48:49], v[34:35], v[44:45], v[48:49] neg_lo:[0,0,1] neg_hi:[0,0,1]
	v_pk_fma_f32 v[34:35], v[34:35], v[46:47], v[38:39]
	v_and_b32_e32 v39, 0xffff0000, v17
	v_lshlrev_b32_e32 v38, 16, v17
	v_and_b32_e32 v17, 0xffff0000, v13
	v_lshlrev_b32_e32 v16, 16, v13
	v_pk_mul_f32 v[12:13], v[40:41], v[16:17]
	v_cvt_pk_bf16_f32 v34, v34, v35
	v_pk_fma_f32 v[12:13], v[36:37], v[38:39], v[12:13] neg_lo:[0,0,1] neg_hi:[0,0,1]
	v_pk_mul_f32 v[38:39], v[40:41], v[38:39]
	v_cvt_pk_bf16_f32 v40, v14, v15
	v_pk_fma_f32 v[16:17], v[36:37], v[16:17], v[38:39]
	v_cvt_pk_bf16_f32 v38, v12, v13
	v_and_b32_e32 v13, 0xffff0000, v2
	v_lshlrev_b32_e32 v12, 16, v2
	v_cvt_pk_bf16_f32 v36, v10, v11
	v_and_b32_e32 v11, 0xffff0000, v6
	v_lshlrev_b32_e32 v10, 16, v6
	s_waitcnt vmcnt(0)
	v_pk_mul_f32 v[14:15], v[30:31], v[12:13]
	v_lshlrev_b32_e32 v6, 16, v3
	v_pk_fma_f32 v[14:15], v[26:27], v[10:11], v[14:15] neg_lo:[0,0,1] neg_hi:[0,0,1]
	v_pk_mul_f32 v[10:11], v[30:31], v[10:11]
	v_cvt_pk_bf16_f32 v35, v16, v17
	v_pk_fma_f32 v[10:11], v[26:27], v[12:13], v[10:11]
	v_and_b32_e32 v13, 0xffff0000, v7
	v_lshlrev_b32_e32 v12, 16, v7
	v_and_b32_e32 v7, 0xffff0000, v3
	v_pk_mul_f32 v[2:3], v[32:33], v[6:7]
	v_and_b32_e32 v17, 0xffff0000, v4
	v_pk_fma_f32 v[2:3], v[28:29], v[12:13], v[2:3] neg_lo:[0,0,1] neg_hi:[0,0,1]
	v_pk_mul_f32 v[12:13], v[32:33], v[12:13]
	v_lshlrev_b32_e32 v16, 16, v4
	v_pk_fma_f32 v[6:7], v[28:29], v[6:7], v[12:13]
	v_and_b32_e32 v13, 0xffff0000, v8
	v_lshlrev_b32_e32 v12, 16, v8
	v_pk_mul_f32 v[26:27], v[22:23], v[16:17]
	v_lshlrev_b32_e32 v8, 16, v5
	v_pk_fma_f32 v[26:27], v[18:19], v[12:13], v[26:27] neg_lo:[0,0,1] neg_hi:[0,0,1]
	v_pk_mul_f32 v[12:13], v[22:23], v[12:13]
	v_cvt_pk_bf16_f32 v37, v48, v49
	v_pk_fma_f32 v[12:13], v[18:19], v[16:17], v[12:13]
	v_and_b32_e32 v17, 0xffff0000, v9
	v_lshlrev_b32_e32 v16, 16, v9
	v_and_b32_e32 v9, 0xffff0000, v5
	v_pk_mul_f32 v[4:5], v[24:25], v[8:9]
	v_mov_b32_e32 v78, v1
	v_pk_fma_f32 v[4:5], v[20:21], v[16:17], v[4:5] neg_lo:[0,0,1] neg_hi:[0,0,1]
	v_pk_mul_f32 v[16:17], v[24:25], v[16:17]
	v_cvt_pk_bf16_f32 v4, v4, v5
	v_cvt_pk_bf16_f32 v5, v10, v11
	v_lshlrev_b32_e32 v10, 16, v37
	v_and_b32_e32 v11, 0xffff0000, v37
	v_pk_fma_f32 v[8:9], v[20:21], v[8:9], v[16:17]
	v_mul_f32_e32 v10, 0x3e0293ee, v10
	v_mul_f32_e32 v11, 0x3e0293ee, v11
	v_cvt_pk_bf16_f32 v8, v8, v9
	v_lshlrev_b32_e32 v9, 16, v0
	v_and_b32_e32 v0, 0xffff0000, v0
	v_cvt_pk_fp8_f32 v79, v10, v11
	v_mul_f32_e32 v9, 0x3e0293ee, v9
	v_mul_f32_e32 v0, 0x3e0293ee, v0
	v_cvt_pk_bf16_f32 v6, v6, v7
	v_cvt_pk_bf16_f32 v7, v12, v13
	v_lshlrev_b32_e32 v13, 16, v38
	v_cvt_pk_fp8_f32 v78, v9, v0
	v_and_b32_e32 v0, 0xffff0000, v38
	v_cvt_pk_bf16_f32 v14, v14, v15
	v_mul_f32_e32 v13, 0x3e0293ee, v13
	v_mul_f32_e32 v0, 0x3e0293ee, v0
	v_cvt_pk_fp8_f32 v79, v13, v0 op_sel:[0,0,1]
	v_lshlrev_b32_e32 v0, 16, v14
	v_and_b32_e32 v10, 0xffff0000, v14
	v_cvt_pk_bf16_f32 v2, v2, v3
	v_cvt_pk_bf16_f32 v3, v26, v27
	v_mul_f32_e32 v0, 0x3e0293ee, v0
	v_mul_f32_e32 v10, 0x3e0293ee, v10
	v_mov_b32_e32 v80, v1
	v_lshlrev_b32_e32 v9, 16, v3
	v_and_b32_e32 v3, 0xffff0000, v3
	v_cvt_pk_fp8_f32 v80, v0, v10
	v_mul_f32_e32 v9, 0x3e0293ee, v9
	v_mul_f32_e32 v3, 0x3e0293ee, v3
	v_mov_b32_e32 v81, v1
	v_lshlrev_b32_e32 v12, 16, v36
	v_and_b32_e32 v15, 0xffff0000, v36
	v_lshlrev_b32_e32 v11, 16, v2
	v_and_b32_e32 v2, 0xffff0000, v2
	v_cvt_pk_fp8_f32 v81, v9, v3
	v_mul_f32_e32 v12, 0x3e0293ee, v12
	v_mul_f32_e32 v15, 0x3e0293ee, v15
	v_mul_f32_e32 v11, 0x3e0293ee, v11
	v_mul_f32_e32 v2, 0x3e0293ee, v2
	v_cvt_pk_fp8_f32 v78, v12, v15 op_sel:[0,0,1]
	v_lshlrev_b32_e32 v12, 16, v4
	v_and_b32_e32 v0, 0xffff0000, v4
	v_cvt_pk_fp8_f32 v80, v11, v2 op_sel:[0,0,1]
	v_lshlrev_b32_e32 v2, 16, v34
	v_and_b32_e32 v4, 0xffff0000, v34
	v_cvt_pk_bf16_f32 v39, v42, v43
	v_mul_f32_e32 v12, 0x3e0293ee, v12
	v_mul_f32_e32 v0, 0x3e0293ee, v0
	v_mul_f32_e32 v2, 0x3e0293ee, v2
	v_mul_f32_e32 v4, 0x3e0293ee, v4
	v_mov_b32_e32 v83, v1
	v_cvt_pk_fp8_f32 v81, v12, v0 op_sel:[0,0,1]
	v_lshlrev_b32_e32 v0, 16, v39
	v_and_b32_e32 v3, 0xffff0000, v39
	v_cvt_pk_fp8_f32 v83, v2, v4
	v_mul_f32_e32 v0, 0x3e0293ee, v0
	v_mul_f32_e32 v3, 0x3e0293ee, v3
	v_mov_b32_e32 v82, v1
	v_lshlrev_b32_e32 v10, 16, v35
	v_cvt_pk_fp8_f32 v82, v0, v3
	v_and_b32_e32 v0, 0xffff0000, v35
	v_mul_f32_e32 v10, 0x3e0293ee, v10
	v_mul_f32_e32 v0, 0x3e0293ee, v0
	v_cvt_pk_fp8_f32 v83, v10, v0 op_sel:[0,0,1]
	v_lshlrev_b32_e32 v0, 16, v5
	v_lshlrev_b32_e32 v2, 16, v7
	v_and_b32_e32 v3, 0xffff0000, v5
	v_and_b32_e32 v4, 0xffff0000, v7
	v_mul_f32_e32 v0, 0x3e0293ee, v0
	v_mul_f32_e32 v2, 0x3e0293ee, v2
	v_mul_f32_e32 v3, 0x3e0293ee, v3
	v_mul_f32_e32 v4, 0x3e0293ee, v4
	v_mov_b32_e32 v84, v1
	v_mov_b32_e32 v85, v1
	v_cvt_pk_fp8_f32 v84, v0, v3
	v_cvt_pk_fp8_f32 v85, v2, v4
	v_lshlrev_b32_e32 v9, 16, v40
	v_and_b32_e32 v11, 0xffff0000, v40
	v_lshlrev_b32_e32 v5, 16, v6
	v_lshlrev_b32_e32 v7, 16, v8
	v_and_b32_e32 v6, 0xffff0000, v6
	v_and_b32_e32 v0, 0xffff0000, v8
	v_mul_f32_e32 v9, 0x3e0293ee, v9
	v_mul_f32_e32 v11, 0x3e0293ee, v11
	v_mul_f32_e32 v5, 0x3e0293ee, v5
	v_mul_f32_e32 v7, 0x3e0293ee, v7
	v_mul_f32_e32 v6, 0x3e0293ee, v6
	v_mul_f32_e32 v0, 0x3e0293ee, v0
	v_cvt_pk_fp8_f32 v82, v9, v11 op_sel:[0,0,1]
	v_cvt_pk_fp8_f32 v84, v5, v6 op_sel:[0,0,1]
	v_cvt_pk_fp8_f32 v85, v7, v0 op_sel:[0,0,1]
	s_waitcnt lgkmcnt(0)
	s_mov_b64 s[10:11], s[52:53]
	s_cmp_eq_u64 vcc, 0
	s_cbranch_scc1 .LBB0_991
; template <bool SLC, class Desc>
; __device__ __forceinline__ void attn_run_frag8(const i64_t (&qf)[4], const unsigned char* __restrict__ KF, const unsigned char* __restrict__ VF, const Desc& desc, int n,
;                                                int lo_in, int hi, int qi, AState& st, int lane) {
;     if (n <= 0) return;
;     Frag8 fa, fb, fc;
;     constexpr int NM = ~(1 << 30);
;     int d0 = desc(0), d1 = desc(n > 1 ? 1 : 0);
;     load_frag8(fa, KF, VF, SLC ? (d0 & 0xfffff) : (d0 & NM), lane);
;     load_frag8(fb, KF, VF, SLC ? (d1 & 0xfffff) : (d1 & NM), lane);
; __device__ __forceinline__ void nsa_unit(int unit, const bf16_t* proj, const bf16_t* kc, const bf16_t* vc, const bf16_t* gn, const float* cs, const float* sn, ...
;     ...
;     { auto desc = [&](int i) { return __builtin_amdgcn_readfirstlane(list[i]); };
;       unsigned long long goff = (unsigned long long)g * S * 128; asm volatile("" : "+s"(goff));
;       attn_run_frag8<true>(q8, (const unsigned char*)kslf + goff, (const unsigned char*)kslf + ((size_t)8 << 20) + goff, desc, nslc, 0, tc, qi, st, lane); }
	v_add_u32_e32 v242, s3, v120
	v_mov_b32_e32 v0, s3
	ds_read_b64 v[2:3], v0 offset:13632
	ds_read_b32 v241, v242 offset:13632
	s_bcnt1_i32_b64 s12, vcc
	s_lshl_b32 s54, s12, 1
	s_add_u32 s12, s69, s10
	s_addc_u32 s13, s70, s11
	s_add_u32 s10, s67, s10
	s_waitcnt lgkmcnt(0)
	v_readfirstlane_b32 s57, v2
	s_addc_u32 s11, s68, s11
	s_lshl_b32 s16, s57, 7
	s_and_b32 s14, s16, 0x7fff800
	s_add_u32 s14, s10, s14
	s_addc_u32 s15, s11, 0
	v_readfirstlane_b32 s92, v3
	v_lshl_add_u64 v[2:3], s[14:15], 0, v[120:121]
	s_and_b32 s14, s16, 0x7fff000
	s_add_u32 s14, s12, s14
	s_addc_u32 s15, s13, 0
	s_lshl_b32 s16, s92, 7
	v_lshl_add_u64 v[246:247], v[2:3], 0, v[120:121]
	global_load_dwordx4 v[138:141], v[246:247], off
	global_load_dwordx4 v[142:145], v[246:247], off offset:1024
	global_load_dwordx4 v[146:149], v[246:247], off offset:2048
	global_load_dwordx4 v[150:153], v[246:247], off offset:3072
	v_lshl_add_u64 v[2:3], s[14:15], 0, v[120:121]
	s_and_b32 s14, s16, 0x7fff800
	s_add_u32 s14, s10, s14
	s_addc_u32 s15, s11, 0
	v_lshl_add_u64 v[244:245], v[2:3], 0, v[120:121]
	global_load_dwordx4 v[90:93], v[244:245], off
	global_load_dwordx4 v[94:97], v[244:245], off offset:1024
	global_load_dwordx4 v[98:101], v[244:245], off offset:2048
	global_load_dwordx4 v[102:105], v[244:245], off offset:3072
	v_lshl_add_u64 v[2:3], s[14:15], 0, v[120:121]
	s_and_b32 s14, s16, 0x7fff000
	s_add_u32 s14, s12, s14
	s_addc_u32 s15, s13, 0
	v_lshl_add_u64 v[246:247], v[2:3], 0, v[120:121]
	global_load_dwordx4 v[154:157], v[246:247], off
	global_load_dwordx4 v[158:161], v[246:247], off offset:1024
	global_load_dwordx4 v[162:165], v[246:247], off offset:2048
	global_load_dwordx4 v[166:169], v[246:247], off offset:3072
	v_lshl_add_u64 v[2:3], s[14:15], 0, v[120:121]
	v_lshl_add_u64 v[244:245], v[2:3], 0, v[120:121]
	global_load_dwordx4 v[106:109], v[244:245], off
	global_load_dwordx4 v[110:113], v[244:245], off offset:1024
	global_load_dwordx4 v[114:117], v[244:245], off offset:2048
	global_load_dwordx4 v[134:137], v[244:245], off offset:3072
	v_mov_b32_e32 v2, v1
	v_mov_b32_e32 v3, v1
	v_mov_b32_e32 v0, v1
	v_mov_b64_e32 v[38:39], v[2:3]
	v_mov_b64_e32 v[42:43], v[2:3]
	v_mov_b64_e32 v[46:47], v[2:3]
	v_mov_b64_e32 v[50:51], v[2:3]
	v_mov_b64_e32 v[54:55], v[2:3]
	v_mov_b64_e32 v[58:59], v[2:3]
	v_mov_b64_e32 v[62:63], v[2:3]
	v_mov_b64_e32 v[66:67], v[2:3]
	v_lshl_add_u64 v[86:87], s[10:11], 0, v[120:121]
	v_lshl_add_u64 v[88:89], s[12:13], 0, v[120:121]
	s_add_i32 s55, s54, -1
	v_mov_b32_e32 v202, 0xf149f2ca
	v_mov_b32_e32 v203, 0
	s_mov_b32 s56, 4
	v_mov_b64_e32 v[36:37], v[0:1]
	v_mov_b64_e32 v[40:41], v[0:1]
	v_mov_b64_e32 v[44:45], v[0:1]
	v_mov_b64_e32 v[48:49], v[0:1]
	v_mov_b64_e32 v[52:53], v[0:1]
	v_mov_b64_e32 v[56:57], v[0:1]
	v_mov_b64_e32 v[60:61], v[0:1]
	v_mov_b64_e32 v[64:65], v[0:1]
	s_branch .LBB0_963

; #define F8_STEP(CUR, NXT2, DC, DN2) do { \
;         if ((DC) & (1 << 30)) step_frag8<SLC, true>(qf, CUR, NXT2, KF, VF, (DC) & NM, (DN2) & NM, lo_in, hi, qi, st, lane); \
;         else step_frag8<SLC, false>(qf, CUR, NXT2, KF, VF, (DC), (DN2) & NM, lo_in, hi, qi, st, lane); } while (0)
; template <bool SLC, class Desc>
; __device__ __forceinline__ void attn_run_frag8(const i64_t (&qf)[4], const unsigned char* __restrict__ KF, const unsigned char* __restrict__ VF, const Desc& desc, int n,
;                                                int lo_in, int hi, int qi, AState& st, int lane) {
;     ...
;     for (int i = 0; i < n; i += 3) {
;         const int d2 = desc(i + 2 < n ? i + 2 : n - 1);
;         F8_STEP(fa, fc, d0, d2);
; __device__ __forceinline__ void nsa_unit(int unit, const bf16_t* proj, const bf16_t* kc, const bf16_t* vc, const bf16_t* gn, const float* cs, const float* sn, ...
;     ...
;     { auto desc = [&](int i) { return __builtin_amdgcn_readfirstlane(list[i]); };
.LBB0_963:
	s_add_i32 s12, s56, -2
	s_cmp_lt_u32 s12, s54
	s_cselect_b64 s[26:27], -1, 0
	s_and_b64 s[10:11], s[26:27], exec
	s_cselect_b32 s10, s12, s55
	s_lshr_b32 s99, s10, 1
	s_and_b32 s98, s10, 1
	s_lshl_b32 s98, s98, 5
	s_nop 3
	v_readlane_b32 s100, v241, s99
	s_nop 3
	s_or_b32 s100, s100, s98
	s_and_b32 s13, s57, 2.0
	s_ashr_i32 s12, s57, 20
	s_mov_b64 s[10:11], -1
	s_cmp_eq_u32 s13, 0
	s_mov_b32 s66, s100
	v_add_f32_e32 v204, 4.0, v202
	s_cbranch_scc0 .LBB0_969
	s_and_b64 vcc, exec, s[10:11]
	s_cbranch_vccnz .LBB0_972

; #define F8_STEP(CUR, NXT2, DC, DN2) do { \
;         if ((DC) & (1 << 30)) step_frag8<SLC, true>(qf, CUR, NXT2, KF, VF, (DC) & NM, (DN2) & NM, lo_in, hi, qi, st, lane); \
;         else step_frag8<SLC, false>(qf, CUR, NXT2, KF, VF, (DC), (DN2) & NM, lo_in, hi, qi, st, lane); } while (0)
; template <bool SLC, class Desc>
; __device__ __forceinline__ void attn_run_frag8(const i64_t (&qf)[4], const unsigned char* __restrict__ KF, const unsigned char* __restrict__ VF, const Desc& desc, int n,
;                                                int lo_in, int hi, int qi, AState& st, int lane) {
;     ...
;     for (int i = 0; i < n; i += 3) {
;         const int d2 = desc(i + 2 < n ? i + 2 : n - 1);
;         F8_STEP(fa, fc, d0, d2);
;         if (i + 1 >= n) break;
;         const int d3 = desc(i + 3 < n ? i + 3 : n - 1);
;         F8_STEP(fb, fa, d1, d3);
; __device__ __forceinline__ void nsa_unit(int unit, const bf16_t* proj, const bf16_t* kc, const bf16_t* vc, const bf16_t* gn, const float* cs, const float* sn, ...
;     ...
;     { auto desc = [&](int i) { return __builtin_amdgcn_readfirstlane(list[i]); };
.LBB0_966:
	s_add_i32 s42, s56, -1
	s_cmp_lt_u32 s42, s54
	s_cselect_b32 s10, s42, s55
	s_lshr_b32 s99, s10, 1
	s_and_b32 s98, s10, 1
	s_lshl_b32 s98, s98, 5
	s_nop 3
	v_readlane_b32 s100, v241, s99
	s_nop 3
	s_or_b32 s100, s100, s98
	s_and_b32 s13, s92, 2.0
	s_ashr_i32 s12, s92, 20
	s_mov_b64 s[10:11], -1
	s_cmp_eq_u32 s13, 0
	s_mov_b32 s57, s100
	v_add_f32_e32 v2, 4.0, v0
	s_cbranch_scc0 .LBB0_976
	s_and_b64 vcc, exec, s[10:11]
	s_cbranch_vccnz .LBB0_979

; #define F8_STEP(CUR, NXT2, DC, DN2) do { \
;         if ((DC) & (1 << 30)) step_frag8<SLC, true>(qf, CUR, NXT2, KF, VF, (DC) & NM, (DN2) & NM, lo_in, hi, qi, st, lane); \
;         else step_frag8<SLC, false>(qf, CUR, NXT2, KF, VF, (DC), (DN2) & NM, lo_in, hi, qi, st, lane); } while (0)
; template <bool SLC, bool NOMASK> ...
;     const int kq = lane >> 4;
;     const int pos0 = SLC ? (dcur & 0xfffff) : dcur;
;     const int lo = SLC ? ((((dcur >> 20) == qi) | ((dcur >> 20) == 4)) ? 0 : (1 << 30)) : lo_in;
;     load_frag8(nxt, KF, VF, SLC ? (dnext & 0xfffff) : dnext, lane);
;     f32x4 sa[2] = {(f32x4){0.f, 0.f, 0.f, 0.f}, (f32x4){0.f, 0.f, 0.f, 0.f}};
; #pragma unroll
;     for (int T = 0; T < 2; ++T)
; #pragma unroll
;         for (int s2 = 0; s2 < 4; ++s2) sa[T] = __builtin_amdgcn_mfma_f32_16x16x32_fp8_fp8(cur.k[T][s2], qf[s2], sa[T], 0, 0, 0);
;     float sc[8]; bool vd[8]; float mx = -1e30f;
;     const bool act = lo == 0 || !SLC;
;     if (NOMASK) {
; #pragma unroll
;         for (int j = 0; j < 8; ++j) { sc[j] = sa[j >> 2][j & 3]; vd[j] = act; }
;         mx = fmaxf(fmaxf(fmaxf(sc[0], sc[1]), fmaxf(sc[2], sc[3])), fmaxf(fmaxf(sc[4], sc[5]), fmaxf(sc[6], sc[7])));
;         mx = act ? mx : -1e30f;
;     } else {
; #pragma unroll
;         for (int T = 0; T < 2; ++T)
; #pragma unroll
;             for (int r = 0; r < 4; ++r) { const int p = pos0 + 16 * T + 4 * kq + r; const bool v = (p >= lo) & (p <= hi); const float x = sa[T][r];
;                 sc[4 * T + r] = x; vd[4 * T + r] = v; mx = v ? fmaxf(mx, x) : mx; }
;     }
;     if (__builtin_amdgcn_ballot_w64(mx > st.m + 4.f) != 0ull) {
;         mx = fmaxf(mx, __shfl_xor(mx, 16)); mx = fmaxf(mx, __shfl_xor(mx, 32));
;         const float mn = fmaxf(st.m, mx), alpha = __builtin_amdgcn_exp2f(st.m - mn); st.m = mn; st.l *= alpha;
; #pragma unroll
;         for (int j = 0; j < 8; ++j) st.o[j] = st.o[j] * alpha;
; template <bool SLC, class Desc>
; __device__ __forceinline__ void attn_run_frag8(const i64_t (&qf)[4], const unsigned char* __restrict__ KF, const unsigned char* __restrict__ VF, const Desc& desc, int n,
;                                                int lo_in, int hi, int qi, AState& st, int lane) {
;     ...
;         const int d4 = desc(i + 4 < n ? i + 4 : n - 1);
;         F8_STEP(fc, fb, d2, d4);
.LBB0_982:
	s_cmp_lt_u32 s56, s54
	s_cselect_b32 s10, s56, s55
	s_lshr_b32 s99, s10, 1
	s_and_b32 s98, s10, 1
	s_lshl_b32 s98, s98, 5
	s_nop 3
	v_readlane_b32 s100, v241, s99
	s_nop 3
	s_or_b32 s100, s100, s98
	s_and_b32 s13, s66, 2.0
	s_ashr_i32 s12, s66, 20
	s_mov_b64 s[10:11], -1
	s_cmp_eq_u32 s13, 0
	s_mov_b32 s92, s100
	v_add_f32_e32 v0, 4.0, v203
	s_cbranch_scc1 .LBB0_986
	s_and_b32 s13, s12, 0xfffffbff
	s_cmp_eq_u32 s13, 4
	s_cselect_b64 s[10:11], -1, 0
	s_lshl_b32 s14, s92, 7
	s_and_b32 s50, s14, 0x7fff800
	v_lshl_add_u64 v[10:11], v[86:87], 0, s[50:51]
	s_and_b32 s50, s14, 0x7fff000
	v_lshl_add_u64 v[246:247], v[10:11], 0, v[120:121]
	global_load_dwordx4 v[154:157], v[246:247], off
	global_load_dwordx4 v[158:161], v[246:247], off offset:1024
	global_load_dwordx4 v[162:165], v[246:247], off offset:2048
	global_load_dwordx4 v[166:169], v[246:247], off offset:3072
	v_lshl_add_u64 v[10:11], v[88:89], 0, s[50:51]
	v_lshl_add_u64 v[244:245], v[10:11], 0, v[120:121]
	global_load_dwordx4 v[106:109], v[244:245], off
	global_load_dwordx4 v[110:113], v[244:245], off offset:1024
	global_load_dwordx4 v[114:117], v[244:245], off offset:2048
	global_load_dwordx4 v[134:137], v[244:245], off offset:3072
	s_waitcnt vmcnt(20)
	v_mfma_f32_16x16x128_f8f6f4 v[2:5], v[186:193], v[78:85], 0
	v_cmp_eq_u32_e32 vcc, s13, v209
	s_or_b64 s[10:11], s[10:11], vcc
	v_mfma_f32_16x16x128_f8f6f4 v[6:9], v[194:201], v[78:85], 0
	v_mov_b32_e32 v202, v203
	v_mov_b32_e32 v133, v204
	s_nop 8
	v_max3_f32 v10, v2, v3, v4
	v_max3_f32 v12, v5, v6, v7
	v_max3_f32 v10, v10, v8, v9
	v_max_f32_e32 v10, v10, v12
	v_cndmask_b32_e64 v34, v220, v10, s[10:11]
	v_cmp_gt_f32_e32 vcc, v34, v0
	s_cbranch_vccz .LBB0_985
	ds_bpermute_b32 v10, v225, v34
	v_max_f32_e32 v11, v34, v34
	s_waitcnt lgkmcnt(0)
	v_max_f32_e32 v10, v10, v10
	v_max_f32_e32 v10, v11, v10
	ds_bpermute_b32 v11, v224, v10
	s_waitcnt lgkmcnt(0)
	v_max3_f32 v202, v203, v10, v11
	v_sub_f32_e32 v10, v203, v202
	v_exp_f32_e32 v34, v10
	s_nop 0
	v_mul_f32_e32 v133, v204, v34
	v_pk_mul_f32 v[38:39], v[38:39], v[34:35] op_sel_hi:[1,0]
	v_pk_mul_f32 v[36:37], v[36:37], v[34:35] op_sel_hi:[1,0]
	v_pk_mul_f32 v[42:43], v[42:43], v[34:35] op_sel_hi:[1,0]
	v_pk_mul_f32 v[40:41], v[40:41], v[34:35] op_sel_hi:[1,0]
	v_pk_mul_f32 v[46:47], v[46:47], v[34:35] op_sel_hi:[1,0]
	v_pk_mul_f32 v[44:45], v[44:45], v[34:35] op_sel_hi:[1,0]
	v_pk_mul_f32 v[50:51], v[50:51], v[34:35] op_sel_hi:[1,0]
	v_pk_mul_f32 v[48:49], v[48:49], v[34:35] op_sel_hi:[1,0]
	v_pk_mul_f32 v[54:55], v[54:55], v[34:35] op_sel_hi:[1,0]
	v_pk_mul_f32 v[52:53], v[52:53], v[34:35] op_sel_hi:[1,0]
	v_pk_mul_f32 v[58:59], v[58:59], v[34:35] op_sel_hi:[1,0]
	v_pk_mul_f32 v[56:57], v[56:57], v[34:35] op_sel_hi:[1,0]
	v_pk_mul_f32 v[62:63], v[62:63], v[34:35] op_sel_hi:[1,0]
	v_pk_mul_f32 v[60:61], v[60:61], v[34:35] op_sel_hi:[1,0]
	v_pk_mul_f32 v[66:67], v[66:67], v[34:35] op_sel_hi:[1,0]
	v_pk_mul_f32 v[64:65], v[64:65], v[34:35] op_sel_hi:[1,0]
